# GEMM4 Epi4g: second-half residual loads issued together with the first half's (one exposed round trip per tile instead of two); final_g loads moved behind the reduction
# speedup vs baseline: 1.0001x; 1.0001x over previous
.LBB0_879:
	s_or_b32 s1, s0, s47
	v_mov_b32_e32 v195, v186
	v_mov_b32_e32 v196, v185
	s_nop 15
	s_nop 15
	s_lshl_b32 s0, s1, 8
	v_add_u32_e32 v194, s55, v196
	v_lshl_add_u32 v174, v195, 3, s69
	v_add_u32_e32 v172, s0, v194
	v_ashrrev_i32_e32 v175, 31, v174
	v_ashrrev_i32_e32 v173, 31, v172
	v_lshl_add_u64 v[182:183], v[174:175], 1, s[10:11]
	v_lshlrev_b64 v[242:243], 2, v[174:175]
	v_lshl_add_u64 v[242:243], s[12:13], 0, v[242:243]
	v_lshlrev_b64 v[128:129], 12, v[172:173]
	v_lshl_add_u64 v[176:177], v[182:183], 0, v[128:129]
	global_load_dwordx4 v[178:181], v[176:177], off
	global_load_dwordx4 v[198:201], v[176:177], off offset:256
	v_add_u32_e32 v170, 16, v172
	v_add_u32_e32 v168, 32, v172
	v_add_u32_e32 v166, 48, v172
	v_ashrrev_i32_e32 v171, 31, v170
	v_ashrrev_i32_e32 v169, 31, v168
	v_ashrrev_i32_e32 v167, 31, v166
	v_lshlrev_b64 v[128:129], 12, v[170:171]
	v_lshlrev_b64 v[130:131], 12, v[168:169]
	v_lshlrev_b64 v[132:133], 12, v[166:167]
	v_lshl_add_u64 v[128:129], v[182:183], 0, v[128:129]
	v_lshl_add_u64 v[130:131], v[182:183], 0, v[130:131]
	v_lshl_add_u64 v[202:203], v[182:183], 0, v[132:133]
	global_load_dwordx4 v[148:151], v[128:129], off
	global_load_dwordx4 v[144:147], v[128:129], off offset:256
	global_load_dwordx4 v[140:143], v[130:131], off
	global_load_dwordx4 v[136:139], v[130:131], off offset:256
	global_load_dwordx4 v[132:135], v[202:203], off
	s_nop 0
	global_load_dwordx4 v[128:131], v[202:203], off offset:256
	v_add_co_u32_e32 v224, vcc, 0x80000, v176
	s_nop 1
	v_addc_co_u32_e32 v225, vcc, 0, v177, vcc
	global_load_dwordx4 v[216:219], v[224:225], off
	global_load_dwordx4 v[220:223], v[224:225], off offset:256
	v_add_co_u32_e32 v252, vcc, 0x90000, v176
	s_nop 1
	v_addc_co_u32_e32 v253, vcc, 0, v177, vcc
	global_load_dwordx4 v[244:247], v[252:253], off
	global_load_dwordx4 v[248:251], v[252:253], off offset:256
	v_add_co_u32_e32 v224, vcc, 0xa0000, v176
	s_nop 1
	v_addc_co_u32_e32 v225, vcc, 0, v177, vcc
	global_load_dwordx4 v[226:229], v[224:225], off
	global_load_dwordx4 v[230:233], v[224:225], off offset:256
	v_add_co_u32_e32 v252, vcc, 0xb0000, v176
	s_nop 1
	v_addc_co_u32_e32 v253, vcc, 0, v177, vcc
	global_load_dwordx4 v[234:237], v[252:253], off
	global_load_dwordx4 v[238:241], v[252:253], off offset:256
	v_and_b32_e32 v202, 64, v191
	v_add_u32_e32 v210, 64, v202
	v_xor_b32_e32 v197, 16, v191
	v_cmp_lt_i32_e32 vcc, v197, v210
	v_cmp_eq_u32_e64 s[4:5], 0, v195
	s_waitcnt vmcnt(8)
	v_lshlrev_b32_e32 v202, 16, v178
	v_and_b32_e32 v203, 0xffff0000, v178
	v_lshlrev_b32_e32 v178, 16, v179
	v_and_b32_e32 v179, 0xffff0000, v179
	v_lshlrev_b32_e32 v206, 16, v198
	v_and_b32_e32 v207, 0xffff0000, v198
	v_lshlrev_b32_e32 v198, 16, v199
	v_and_b32_e32 v199, 0xffff0000, v199
	v_lshlrev_b32_e32 v204, 16, v180
	v_and_b32_e32 v205, 0xffff0000, v180
	v_lshlrev_b32_e32 v208, 16, v200
	v_and_b32_e32 v209, 0xffff0000, v200
	v_pk_add_f32 v[126:127], v[126:127], v[178:179]
	v_pk_add_f32 v[124:125], v[124:125], v[202:203]
	v_pk_add_f32 v[118:119], v[118:119], v[198:199]
	v_pk_add_f32 v[116:117], v[116:117], v[206:207]
	v_lshlrev_b32_e32 v180, 16, v181
	v_and_b32_e32 v181, 0xffff0000, v181
	v_lshlrev_b32_e32 v200, 16, v201
	v_and_b32_e32 v201, 0xffff0000, v201
	v_pk_add_f32 v[120:121], v[120:121], v[204:205]
	v_pk_add_f32 v[112:113], v[112:113], v[208:209]
	v_mul_f32_e32 v178, v125, v125
	v_mul_f32_e32 v179, v127, v127
	v_mul_f32_e32 v198, v117, v117
	v_mul_f32_e32 v199, v119, v119
	v_pk_add_f32 v[122:123], v[122:123], v[180:181]
	v_pk_add_f32 v[114:115], v[114:115], v[200:201]
	v_mul_f32_e32 v180, v121, v121
	v_mul_f32_e32 v200, v113, v113
	v_fmac_f32_e32 v178, v124, v124
	v_fmac_f32_e32 v179, v126, v126
	v_fmac_f32_e32 v198, v116, v116
	v_fmac_f32_e32 v199, v118, v118
	v_mul_f32_e32 v181, v123, v123
	v_mul_f32_e32 v201, v115, v115
	v_fmac_f32_e32 v180, v120, v120
	v_fmac_f32_e32 v200, v112, v112
	v_add_f32_e32 v178, v178, v179
	v_add_f32_e32 v179, v198, v199
	v_fmac_f32_e32 v181, v122, v122
	v_fmac_f32_e32 v201, v114, v114
	v_add_f32_e32 v178, v180, v178
	v_add_f32_e32 v179, v200, v179
	v_cndmask_b32_e32 v197, v191, v197, vcc
	v_add_f32_e32 v178, v181, v178
	v_add_f32_e32 v179, v201, v179
	v_lshlrev_b32_e32 v197, 2, v197
	v_add_f32_e32 v178, v178, v179
	ds_bpermute_b32 v179, v197, v178
	v_xor_b32_e32 v180, 32, v191
	v_cmp_lt_i32_e32 vcc, v180, v210
	s_waitcnt lgkmcnt(0)
	v_add_f32_e32 v178, v178, v179
	v_cndmask_b32_e32 v180, v191, v180, vcc
	v_lshlrev_b32_e32 v198, 2, v180
	ds_bpermute_b32 v179, v198, v178
	s_and_saveexec_b64 s[38:39], s[4:5]
	s_cbranch_execz .LBB0_881
	s_waitcnt lgkmcnt(0)
	v_add_f32_e32 v178, v178, v179
	v_lshl_add_u32 v179, v194, 4, s60
	ds_write_b32 v179, v178

.LBB0_887:
	s_or_b64 exec, exec, s[38:39]
	v_add_co_u32_e32 v64, vcc, 0x80000, v176
	v_add_u32_e32 v180, 0x90, v172
	s_waitcnt lgkmcnt(0)
	v_addc_co_u32_e32 v65, vcc, 0, v177, vcc
	v_lshl_add_u64 v[64:65], v[176:177], 0, s[34:35]
	v_add_u32_e32 v178, 0xa0, v172
	v_add_u32_e32 v176, 0xb0, v172
	v_ashrrev_i32_e32 v181, 31, v180
	v_ashrrev_i32_e32 v179, 31, v178
	v_ashrrev_i32_e32 v177, 31, v176
	v_lshlrev_b64 v[64:65], 12, v[180:181]
	v_lshlrev_b64 v[66:67], 12, v[178:179]
	v_lshlrev_b64 v[68:69], 12, v[176:177]
	v_lshl_add_u64 v[64:65], v[182:183], 0, v[64:65]
	v_lshl_add_u64 v[66:67], v[182:183], 0, v[66:67]
	v_lshl_add_u64 v[182:183], v[182:183], 0, v[68:69]
	s_nop 0
	s_waitcnt vmcnt(7)
	v_lshlrev_b32_e32 v182, 16, v216
	v_and_b32_e32 v183, 0xffff0000, v216
	v_lshlrev_b32_e32 v200, 16, v217
	v_and_b32_e32 v201, 0xffff0000, v217
	s_waitcnt vmcnt(6)
	v_lshlrev_b32_e32 v210, 16, v220
	v_and_b32_e32 v211, 0xffff0000, v220
	v_lshlrev_b32_e32 v204, 16, v221
	v_and_b32_e32 v205, 0xffff0000, v221
	v_lshlrev_b32_e32 v208, 16, v218
	v_and_b32_e32 v209, 0xffff0000, v218
	v_lshlrev_b32_e32 v202, 16, v219
	v_and_b32_e32 v203, 0xffff0000, v219
	v_lshlrev_b32_e32 v212, 16, v222
	v_and_b32_e32 v213, 0xffff0000, v222
	v_pk_add_f32 v[62:63], v[62:63], v[200:201]
	v_pk_add_f32 v[60:61], v[60:61], v[182:183]
	v_pk_add_f32 v[54:55], v[54:55], v[204:205]
	v_pk_add_f32 v[52:53], v[52:53], v[210:211]
	v_lshlrev_b32_e32 v206, 16, v223
	v_and_b32_e32 v207, 0xffff0000, v223
	v_pk_add_f32 v[58:59], v[58:59], v[202:203]
	v_pk_add_f32 v[56:57], v[56:57], v[208:209]
	v_pk_add_f32 v[48:49], v[48:49], v[212:213]
	v_mul_f32_e32 v182, v61, v61
	v_mul_f32_e32 v183, v63, v63
	v_mul_f32_e32 v201, v53, v53
	v_mul_f32_e32 v202, v55, v55
	v_pk_add_f32 v[50:51], v[50:51], v[206:207]
	v_mul_f32_e32 v199, v57, v57
	v_mul_f32_e32 v203, v49, v49
	v_fmac_f32_e32 v182, v60, v60
	v_fmac_f32_e32 v183, v62, v62
	v_fmac_f32_e32 v201, v52, v52
	v_fmac_f32_e32 v202, v54, v54
	v_mul_f32_e32 v200, v59, v59
	v_mul_f32_e32 v204, v51, v51
	v_fmac_f32_e32 v199, v56, v56
	v_fmac_f32_e32 v203, v48, v48
	v_add_f32_e32 v182, v182, v183
	v_add_f32_e32 v183, v201, v202
	v_fmac_f32_e32 v200, v58, v58
	v_fmac_f32_e32 v204, v50, v50
	v_add_f32_e32 v182, v199, v182
	v_add_f32_e32 v183, v203, v183
	v_add_f32_e32 v182, v200, v182
	v_add_f32_e32 v183, v204, v183
	v_add_f32_e32 v182, v182, v183
	ds_bpermute_b32 v183, v197, v182
	s_waitcnt lgkmcnt(0)
	v_add_f32_e32 v182, v182, v183
	ds_bpermute_b32 v183, v198, v182
	s_and_saveexec_b64 s[38:39], s[4:5]
	s_cbranch_execz .LBB0_889
	v_lshl_add_u32 v199, v194, 4, s64
	s_waitcnt lgkmcnt(0)
	v_add_f32_e32 v182, v182, v183
	ds_write_b32 v199, v182
.LBB0_889:
	s_or_b64 exec, exec, s[38:39]
	s_waitcnt vmcnt(5)
	v_lshlrev_b32_e32 v182, 16, v244
	s_waitcnt lgkmcnt(0)
	v_and_b32_e32 v183, 0xffff0000, v244
	v_lshlrev_b32_e32 v84, 16, v245
	v_and_b32_e32 v85, 0xffff0000, v245
	v_pk_add_f32 v[46:47], v[46:47], v[84:85]
	v_pk_add_f32 v[44:45], v[44:45], v[182:183]
	v_lshlrev_b32_e32 v84, 16, v246
	v_and_b32_e32 v85, 0xffff0000, v246
	v_pk_add_f32 v[40:41], v[40:41], v[84:85]
	v_mul_f32_e32 v84, v45, v45
	v_mul_f32_e32 v85, v47, v47
	v_fmac_f32_e32 v84, v44, v44
	v_fmac_f32_e32 v85, v46, v46
	v_lshlrev_b32_e32 v86, 16, v247
	v_and_b32_e32 v87, 0xffff0000, v247
	v_add_f32_e32 v84, v84, v85
	v_mul_f32_e32 v85, v41, v41
	v_pk_add_f32 v[42:43], v[42:43], v[86:87]
	v_fmac_f32_e32 v85, v40, v40
	v_add_f32_e32 v84, v85, v84
	v_mul_f32_e32 v85, v43, v43
	v_fmac_f32_e32 v85, v42, v42
	v_add_f32_e32 v86, v85, v84
	s_waitcnt vmcnt(4)
	v_lshlrev_b32_e32 v84, 16, v248
	v_and_b32_e32 v85, 0xffff0000, v248
	v_lshlrev_b32_e32 v80, 16, v249
	v_and_b32_e32 v81, 0xffff0000, v249
	v_pk_add_f32 v[38:39], v[38:39], v[80:81]
	v_pk_add_f32 v[36:37], v[36:37], v[84:85]
	v_lshlrev_b32_e32 v80, 16, v250
	v_and_b32_e32 v81, 0xffff0000, v250
	v_pk_add_f32 v[32:33], v[32:33], v[80:81]
	v_mul_f32_e32 v80, v37, v37
	v_mul_f32_e32 v81, v39, v39
	v_fmac_f32_e32 v80, v36, v36
	v_fmac_f32_e32 v81, v38, v38
	v_lshlrev_b32_e32 v82, 16, v251
	v_and_b32_e32 v83, 0xffff0000, v251
	v_add_f32_e32 v80, v80, v81
	v_mul_f32_e32 v81, v33, v33
	v_pk_add_f32 v[34:35], v[34:35], v[82:83]
	v_fmac_f32_e32 v81, v32, v32
	v_add_f32_e32 v80, v81, v80
	v_mul_f32_e32 v81, v35, v35
	v_fmac_f32_e32 v81, v34, v34
	v_add_f32_e32 v80, v81, v80
	v_add_f32_e32 v80, v86, v80
	ds_bpermute_b32 v81, v197, v80
	s_waitcnt lgkmcnt(0)
	v_add_f32_e32 v80, v80, v81
	ds_bpermute_b32 v81, v198, v80
	s_and_saveexec_b64 s[38:39], s[4:5]
	s_cbranch_execz .LBB0_891
	v_lshl_add_u32 v82, v194, 4, s65
	s_waitcnt lgkmcnt(0)
	v_add_f32_e32 v80, v80, v81
	ds_write_b32 v82, v80
.LBB0_891:
	s_or_b64 exec, exec, s[38:39]
	s_waitcnt vmcnt(3)
	v_lshlrev_b32_e32 v80, 16, v226
	s_waitcnt lgkmcnt(0)
	v_and_b32_e32 v81, 0xffff0000, v226
	v_lshlrev_b32_e32 v76, 16, v227
	v_and_b32_e32 v77, 0xffff0000, v227
	v_pk_add_f32 v[30:31], v[30:31], v[76:77]
	v_pk_add_f32 v[28:29], v[28:29], v[80:81]
	v_lshlrev_b32_e32 v76, 16, v228
	v_and_b32_e32 v77, 0xffff0000, v228
	v_pk_add_f32 v[24:25], v[24:25], v[76:77]
	v_mul_f32_e32 v76, v29, v29
	v_mul_f32_e32 v77, v31, v31
	v_fmac_f32_e32 v76, v28, v28
	v_fmac_f32_e32 v77, v30, v30
	v_lshlrev_b32_e32 v78, 16, v229
	v_and_b32_e32 v79, 0xffff0000, v229
	v_add_f32_e32 v76, v76, v77
	v_mul_f32_e32 v77, v25, v25
	v_pk_add_f32 v[26:27], v[26:27], v[78:79]
	v_fmac_f32_e32 v77, v24, v24
	v_add_f32_e32 v76, v77, v76
	v_mul_f32_e32 v77, v27, v27
	v_fmac_f32_e32 v77, v26, v26
	v_add_f32_e32 v78, v77, v76
	s_waitcnt vmcnt(2)
	v_lshlrev_b32_e32 v76, 16, v230
	v_and_b32_e32 v77, 0xffff0000, v230
	v_lshlrev_b32_e32 v72, 16, v231
	v_and_b32_e32 v73, 0xffff0000, v231
	v_pk_add_f32 v[22:23], v[22:23], v[72:73]
	v_pk_add_f32 v[20:21], v[20:21], v[76:77]
	v_lshlrev_b32_e32 v72, 16, v232
	v_and_b32_e32 v73, 0xffff0000, v232
	v_pk_add_f32 v[16:17], v[16:17], v[72:73]
	v_mul_f32_e32 v72, v21, v21
	v_mul_f32_e32 v73, v23, v23
	v_fmac_f32_e32 v72, v20, v20
	v_fmac_f32_e32 v73, v22, v22
	v_lshlrev_b32_e32 v74, 16, v233
	v_and_b32_e32 v75, 0xffff0000, v233
	v_add_f32_e32 v72, v72, v73
	v_mul_f32_e32 v73, v17, v17
	v_pk_add_f32 v[18:19], v[18:19], v[74:75]
	v_fmac_f32_e32 v73, v16, v16
	v_add_f32_e32 v72, v73, v72
	v_mul_f32_e32 v73, v19, v19
	v_fmac_f32_e32 v73, v18, v18
	v_add_f32_e32 v72, v73, v72
	v_add_f32_e32 v72, v78, v72
	ds_bpermute_b32 v73, v197, v72
	s_waitcnt lgkmcnt(0)
	v_add_f32_e32 v72, v72, v73
	ds_bpermute_b32 v73, v198, v72
	s_and_saveexec_b64 s[38:39], s[4:5]
	s_cbranch_execz .LBB0_893
	v_lshl_add_u32 v74, v194, 4, s66
	s_waitcnt lgkmcnt(0)
	v_add_f32_e32 v72, v72, v73
	ds_write_b32 v74, v72
.LBB0_893:
	s_or_b64 exec, exec, s[38:39]
	s_waitcnt vmcnt(1)
	v_lshlrev_b32_e32 v72, 16, v234
	s_waitcnt lgkmcnt(0)
	v_and_b32_e32 v73, 0xffff0000, v234
	v_lshlrev_b32_e32 v68, 16, v235
	v_and_b32_e32 v69, 0xffff0000, v235
	v_pk_add_f32 v[68:69], v[14:15], v[68:69]
	v_pk_add_f32 v[72:73], v[12:13], v[72:73]
	v_lshlrev_b32_e32 v12, 16, v236
	v_and_b32_e32 v13, 0xffff0000, v236
	v_pk_add_f32 v[74:75], v[8:9], v[12:13]
	v_mul_f32_e32 v8, v73, v73
	v_mul_f32_e32 v9, v69, v69
	v_fmac_f32_e32 v8, v72, v72
	v_fmac_f32_e32 v9, v68, v68
	v_lshlrev_b32_e32 v14, 16, v237
	v_and_b32_e32 v15, 0xffff0000, v237
	v_add_f32_e32 v8, v8, v9
	v_mul_f32_e32 v9, v75, v75
	v_pk_add_f32 v[70:71], v[10:11], v[14:15]
	v_fmac_f32_e32 v9, v74, v74
	v_add_f32_e32 v8, v9, v8
	v_mul_f32_e32 v9, v71, v71
	v_fmac_f32_e32 v9, v70, v70
	v_add_f32_e32 v76, v9, v8
	s_waitcnt vmcnt(0)
	v_lshlrev_b32_e32 v8, 16, v238
	v_and_b32_e32 v9, 0xffff0000, v238
	v_lshlrev_b32_e32 v10, 16, v239
	v_and_b32_e32 v11, 0xffff0000, v239
	v_pk_add_f32 v[10:11], v[6:7], v[10:11]
	v_pk_add_f32 v[14:15], v[4:5], v[8:9]
	v_lshlrev_b32_e32 v4, 16, v240
	v_and_b32_e32 v5, 0xffff0000, v240
	v_pk_add_f32 v[12:13], v[0:1], v[4:5]
	v_mul_f32_e32 v0, v15, v15
	v_mul_f32_e32 v1, v11, v11
	v_fmac_f32_e32 v0, v14, v14
	v_fmac_f32_e32 v1, v10, v10
	v_lshlrev_b32_e32 v6, 16, v241
	v_and_b32_e32 v7, 0xffff0000, v241
	v_add_f32_e32 v0, v0, v1
	v_mul_f32_e32 v1, v13, v13
	v_pk_add_f32 v[8:9], v[2:3], v[6:7]
	v_fmac_f32_e32 v1, v12, v12
	v_add_f32_e32 v0, v1, v0
	v_mul_f32_e32 v1, v9, v9
	v_fmac_f32_e32 v1, v8, v8
	v_add_f32_e32 v0, v1, v0
	v_add_f32_e32 v0, v76, v0
	ds_bpermute_b32 v1, v197, v0
	s_waitcnt lgkmcnt(0)
	v_add_f32_e32 v0, v0, v1
	ds_bpermute_b32 v1, v198, v0
	s_and_saveexec_b64 s[38:39], s[4:5]
	s_cbranch_execz .LBB0_895
	v_lshl_add_u32 v2, v194, 4, s67
	s_waitcnt lgkmcnt(0)
	v_add_f32_e32 v0, v0, v1
	ds_write_b32 v2, v0
.LBB0_895:
	s_or_b64 exec, exec, s[38:39]
	v_lshl_add_u32 v2, v195, 4, v196
	global_load_dwordx4 v[226:229], v[242:243], off
	global_load_dwordx4 v[230:233], v[242:243], off offset:16
	global_load_dwordx4 v[234:237], v[242:243], off offset:512
	global_load_dwordx4 v[238:241], v[242:243], off offset:528
	s_waitcnt lgkmcnt(0)
	s_barrier
	v_add_u32_e32 v0, s59, v2
	v_cmp_gt_i32_e64 s[4:5], s58, v0
	s_waitcnt lgkmcnt(0)
	v_ashrrev_i32_e32 v1, 31, v0
	s_and_saveexec_b64 s[38:39], s[4:5]
	s_cbranch_execz .LBB0_899
	v_lshl_add_u32 v3, v0, 4, 0
	v_add_u32_e32 v3, 0x20000, v3
	ds_read_b128 v[4:7], v3
	s_lshl_b32 s3, s1, 3
	s_or_b32 s40, s3, s46
	s_ashr_i32 s41, s40, 31
	s_lshl_b64 s[40:41], s[40:41], 10
	s_add_u32 s40, s20, s40
	s_waitcnt lgkmcnt(0)
	v_mov_b32_e32 v66, v5
	v_mov_b32_e32 v67, v6
	v_mov_b32_e32 v5, v7
	s_addc_u32 s41, s21, s41
	v_pk_add_f32 v[4:5], v[66:67], v[4:5]
	v_lshl_add_u64 v[64:65], v[0:1], 2, s[40:41]
	v_pk_add_f32 v[4:5], v[4:5], v[4:5] op_sel:[0,1] op_sel_hi:[1,0]
	global_store_dword v[64:65], v4, off sc1
	s_waitcnt vmcnt(0)
	v_cmp_eq_u32_e32 vcc, 0, v2
	s_and_b64 exec, exec, vcc
	s_cbranch_execz .LBB0_899
	s_mov_b64 s[40:41], exec
	v_mbcnt_lo_u32_b32 v3, s40, 0
	v_mbcnt_hi_u32_b32 v3, s41, v3
	v_cmp_eq_u32_e32 vcc, 0, v3
	s_and_b64 s[42:43], exec, vcc
	s_mov_b64 exec, s[42:43]
	s_cbranch_execz .LBB0_899
	s_lshl_b32 s42, s1, 6
	s_ashr_i32 s43, s42, 31
	s_lshl_b64 s[42:43], s[42:43], 2
	s_add_u32 s42, s53, s42
	s_addc_u32 s43, s54, s43
	s_bcnt1_i32_b64 s3, s[40:41]
	v_mov_b32_e32 v3, s3
	global_atomic_add v155, v3, s[42:43]
